# baseline (speedup 1.0000x reference)
; __device__ __forceinline__ unsigned pack2(float a, float b) { return (unsigned)f2bf(a) | ((unsigned)f2bf(b) << 16); }
; template <int DH, int MODE>
; __device__ void attn_item(const Params& p, int layer, int b, int blk, int head, char* smem) {
;     ...
;         float other = __shfl_xor(run, 1);
;         float offs = m_run + (half == 0 ? other : 0.f);
; #pragma unroll 2
;         for (int s8 = 0; s8 < 4; ++s8) {
;           float4 va = s4[2 * s8], vb = s4[2 * s8 + 1];
;           float e[8] = {va.x, va.y, va.z, va.w, vb.x, vb.y, vb.z, vb.w};
;           float pv[8];
; #pragma unroll
;           for (int k = 0; k < 8; ++k) {
;             bool valid = (kpb + s8 * 8 + k) < qpos;
;             pv[k] = valid ? __builtin_amdgcn_exp2f(e[k] + offs) : 0.f;
;           }
;           uint4 ov;
;           ov.x = pack2(pv[0], pv[1]); ov.y = pack2(pv[2], pv[3]);
;           ov.z = pack2(pv[4], pv[5]); ov.w = pack2(pv[6], pv[7]);
;           *reinterpret_cast<uint4*>(prow + s8 * 16) = ov;
;         }
.Lsb_p1done_3:
	ds_bpermute_b32 v147, v163, v146
	s_mov_b32 s85, 0
	v_mov_b32_e32 v175, v168
	v_mov_b32_e32 v177, v167
	s_waitcnt lgkmcnt(0)
	v_cndmask_b32_e64 v148, 0, v147, s[6:7]
	v_add_f32_e32 v176, v174, v148
	v_sub_u32_e32 v212, v144, v173
	v_add_u32_e32 v212, 0xffffc040, v212
	v_cmp_lt_i32_e32 vcc, 31, v212
	s_cmp_eq_u64 vcc, exec
	s_cbranch_scc1 .Lsb_p2fast_3
	v_add_f32_e32 v180, v176, v180
	v_add_f32_e32 v181, v176, v181
	v_add_f32_e32 v182, v176, v182
	v_exp_f32_e32 v180, v180
	v_exp_f32_e32 v181, v181
	v_exp_f32_e32 v182, v182
	v_cmp_lt_i32_e32 vcc, 0, v212
	v_cmp_lt_i32_e64 s[92:93], 1, v212
	v_cmp_lt_i32_e64 s[94:95], 2, v212
	v_cndmask_b32_e32 v180, 0, v180, vcc
	v_cndmask_b32_e64 v181, 0, v181, s[92:93]
	v_cndmask_b32_e64 v182, 0, v182, s[94:95]
	v_add_f32_e32 v183, v176, v183
	v_add_f32_e32 v184, v176, v184
	v_add_f32_e32 v185, v176, v185
	v_exp_f32_e32 v183, v183
	v_exp_f32_e32 v184, v184
	v_exp_f32_e32 v185, v185
	v_cmp_lt_i32_e32 vcc, 3, v212
	v_cmp_lt_i32_e64 s[92:93], 4, v212
	v_cmp_lt_i32_e64 s[94:95], 5, v212
	v_cndmask_b32_e32 v183, 0, v183, vcc
	v_cndmask_b32_e64 v184, 0, v184, s[92:93]
	v_cndmask_b32_e64 v185, 0, v185, s[94:95]
	v_add_f32_e32 v186, v176, v186
	v_add_f32_e32 v187, v176, v187
	v_add_f32_e32 v188, v176, v188
	v_exp_f32_e32 v186, v186
	v_exp_f32_e32 v187, v187
	v_exp_f32_e32 v188, v188
	v_cmp_lt_i32_e32 vcc, 6, v212
	v_cmp_lt_i32_e64 s[92:93], 7, v212
	v_cmp_lt_i32_e64 s[94:95], 8, v212
	v_cndmask_b32_e32 v186, 0, v186, vcc
	v_cndmask_b32_e64 v187, 0, v187, s[92:93]
	v_cndmask_b32_e64 v188, 0, v188, s[94:95]
	v_add_f32_e32 v189, v176, v189
	v_add_f32_e32 v190, v176, v190
	v_add_f32_e32 v191, v176, v191
	v_exp_f32_e32 v189, v189
	v_exp_f32_e32 v190, v190
	v_exp_f32_e32 v191, v191
	v_cmp_lt_i32_e32 vcc, 9, v212
	v_cmp_lt_i32_e64 s[92:93], 10, v212
	v_cmp_lt_i32_e64 s[94:95], 11, v212
	v_cndmask_b32_e32 v189, 0, v189, vcc
	v_cndmask_b32_e64 v190, 0, v190, s[92:93]
	v_cndmask_b32_e64 v191, 0, v191, s[94:95]
	v_add_f32_e32 v192, v176, v192
	v_add_f32_e32 v193, v176, v193
	v_add_f32_e32 v194, v176, v194
	v_exp_f32_e32 v192, v192
	v_exp_f32_e32 v193, v193
	v_exp_f32_e32 v194, v194
	v_cmp_lt_i32_e32 vcc, 12, v212
	v_cmp_lt_i32_e64 s[92:93], 13, v212
	v_cmp_lt_i32_e64 s[94:95], 14, v212
	v_cndmask_b32_e32 v192, 0, v192, vcc
	v_cndmask_b32_e64 v193, 0, v193, s[92:93]
	v_cndmask_b32_e64 v194, 0, v194, s[94:95]
	v_add_f32_e32 v195, v176, v195
	v_add_f32_e32 v196, v176, v196
	v_add_f32_e32 v197, v176, v197
	v_exp_f32_e32 v195, v195
	v_exp_f32_e32 v196, v196
	v_exp_f32_e32 v197, v197
	v_cmp_lt_i32_e32 vcc, 15, v212
	v_cmp_lt_i32_e64 s[92:93], 16, v212
	v_cmp_lt_i32_e64 s[94:95], 17, v212
	v_cndmask_b32_e32 v195, 0, v195, vcc
	v_cndmask_b32_e64 v196, 0, v196, s[92:93]
	v_cndmask_b32_e64 v197, 0, v197, s[94:95]
	v_add_f32_e32 v198, v176, v198
	v_add_f32_e32 v199, v176, v199
	v_add_f32_e32 v200, v176, v200
	v_exp_f32_e32 v198, v198
	v_exp_f32_e32 v199, v199
	v_exp_f32_e32 v200, v200
	v_cmp_lt_i32_e32 vcc, 18, v212
	v_cmp_lt_i32_e64 s[92:93], 19, v212
	v_cmp_lt_i32_e64 s[94:95], 20, v212
	v_cndmask_b32_e32 v198, 0, v198, vcc
	v_cndmask_b32_e64 v199, 0, v199, s[92:93]
	v_cndmask_b32_e64 v200, 0, v200, s[94:95]
	v_add_f32_e32 v201, v176, v201
	v_add_f32_e32 v202, v176, v202
	v_add_f32_e32 v203, v176, v203
	v_exp_f32_e32 v201, v201
	v_exp_f32_e32 v202, v202
	v_exp_f32_e32 v203, v203
	v_cmp_lt_i32_e32 vcc, 21, v212
	v_cmp_lt_i32_e64 s[92:93], 22, v212
	v_cmp_lt_i32_e64 s[94:95], 23, v212
	v_cndmask_b32_e32 v201, 0, v201, vcc
	v_cndmask_b32_e64 v202, 0, v202, s[92:93]
	v_cndmask_b32_e64 v203, 0, v203, s[94:95]
	v_add_f32_e32 v204, v176, v204
	v_add_f32_e32 v205, v176, v205
	v_add_f32_e32 v206, v176, v206
	v_exp_f32_e32 v204, v204
	v_exp_f32_e32 v205, v205
	v_exp_f32_e32 v206, v206
	v_cmp_lt_i32_e32 vcc, 24, v212
	v_cmp_lt_i32_e64 s[92:93], 25, v212
	v_cmp_lt_i32_e64 s[94:95], 26, v212
	v_cndmask_b32_e32 v204, 0, v204, vcc
	v_cndmask_b32_e64 v205, 0, v205, s[92:93]
	v_cndmask_b32_e64 v206, 0, v206, s[94:95]
	v_add_f32_e32 v207, v176, v207
	v_add_f32_e32 v208, v176, v208
	v_add_f32_e32 v209, v176, v209
	v_exp_f32_e32 v207, v207
	v_exp_f32_e32 v208, v208
	v_exp_f32_e32 v209, v209
	v_cmp_lt_i32_e32 vcc, 27, v212
	v_cmp_lt_i32_e64 s[92:93], 28, v212
	v_cmp_lt_i32_e64 s[94:95], 29, v212
	v_cndmask_b32_e32 v207, 0, v207, vcc
	v_cndmask_b32_e64 v208, 0, v208, s[92:93]
	v_cndmask_b32_e64 v209, 0, v209, s[94:95]
	v_add_f32_e32 v210, v176, v210
	v_add_f32_e32 v211, v176, v211
	v_exp_f32_e32 v210, v210
	v_exp_f32_e32 v211, v211
	v_cmp_lt_i32_e32 vcc, 30, v212
	v_cmp_lt_i32_e64 s[92:93], 31, v212
	s_nop 0
	v_cndmask_b32_e32 v210, 0, v210, vcc
	v_cndmask_b32_e64 v211, 0, v211, s[92:93]
	v_cvt_pk_bf16_f32 v148, v180, v181
	v_cvt_pk_bf16_f32 v149, v182, v183
	v_cvt_pk_bf16_f32 v150, v184, v185
	v_cvt_pk_bf16_f32 v151, v186, v187
	ds_write_b128 v175, v[148:151]
	v_cvt_pk_bf16_f32 v214, v188, v189
	v_cvt_pk_bf16_f32 v215, v190, v191
	v_cvt_pk_bf16_f32 v216, v192, v193
	v_cvt_pk_bf16_f32 v217, v194, v195
	ds_write_b128 v175, v[214:217] offset:16
	v_cvt_pk_bf16_f32 v148, v196, v197
	v_cvt_pk_bf16_f32 v149, v198, v199
	v_cvt_pk_bf16_f32 v150, v200, v201
	v_cvt_pk_bf16_f32 v151, v202, v203
	ds_write_b128 v175, v[148:151] offset:32
	v_cvt_pk_bf16_f32 v214, v204, v205
	v_cvt_pk_bf16_f32 v215, v206, v207
	v_cvt_pk_bf16_f32 v216, v208, v209
	v_cvt_pk_bf16_f32 v217, v210, v211
	ds_write_b128 v175, v[214:217] offset:48
	s_branch .LBB0_213
; __device__ __forceinline__ unsigned pack2(float a, float b) { return (unsigned)f2bf(a) | ((unsigned)f2bf(b) << 16); }
; template <int DH, int MODE>
; __device__ void attn_item(const Params& p, int layer, int b, int blk, int head, char* smem) {
;     ...
; #pragma unroll 2
;         for (int s8 = 0; s8 < 4; ++s8) {
;           float4 va = s4[2 * s8], vb = s4[2 * s8 + 1];
;           float e[8] = {va.x, va.y, va.z, va.w, vb.x, vb.y, vb.z, vb.w};
;           float pv[8];
; #pragma unroll
;           for (int k = 0; k < 8; ++k) {
;             bool valid = (kpb + s8 * 8 + k) < qpos;
;             pv[k] = valid ? __builtin_amdgcn_exp2f(e[k] + offs) : 0.f;
;           }
;           uint4 ov;
;           ov.x = pack2(pv[0], pv[1]); ov.y = pack2(pv[2], pv[3]);
;           ov.z = pack2(pv[4], pv[5]); ov.w = pack2(pv[6], pv[7]);
;           *reinterpret_cast<uint4*>(prow + s8 * 16) = ov;
;         }
.Lsb_p2fast_3:
	v_add_f32_e32 v180, v176, v180
	v_add_f32_e32 v181, v176, v181
	v_add_f32_e32 v182, v176, v182
	v_add_f32_e32 v183, v176, v183
	v_exp_f32_e32 v180, v180
	v_exp_f32_e32 v181, v181
	v_exp_f32_e32 v182, v182
	v_exp_f32_e32 v183, v183
	v_add_f32_e32 v184, v176, v184
	v_add_f32_e32 v185, v176, v185
	v_add_f32_e32 v186, v176, v186
	v_add_f32_e32 v187, v176, v187
	v_exp_f32_e32 v184, v184
	v_exp_f32_e32 v185, v185
	v_exp_f32_e32 v186, v186
	v_exp_f32_e32 v187, v187
	v_add_f32_e32 v188, v176, v188
	v_add_f32_e32 v189, v176, v189
	v_add_f32_e32 v190, v176, v190
	v_add_f32_e32 v191, v176, v191
	v_exp_f32_e32 v188, v188
	v_exp_f32_e32 v189, v189
	v_exp_f32_e32 v190, v190
	v_exp_f32_e32 v191, v191
	v_add_f32_e32 v192, v176, v192
	v_add_f32_e32 v193, v176, v193
	v_add_f32_e32 v194, v176, v194
	v_add_f32_e32 v195, v176, v195
	v_exp_f32_e32 v192, v192
	v_exp_f32_e32 v193, v193
	v_exp_f32_e32 v194, v194
	v_exp_f32_e32 v195, v195
	v_add_f32_e32 v196, v176, v196
	v_add_f32_e32 v197, v176, v197
	v_add_f32_e32 v198, v176, v198
	v_add_f32_e32 v199, v176, v199
	v_exp_f32_e32 v196, v196
	v_exp_f32_e32 v197, v197
	v_exp_f32_e32 v198, v198
	v_exp_f32_e32 v199, v199
	v_add_f32_e32 v200, v176, v200
	v_add_f32_e32 v201, v176, v201
	v_add_f32_e32 v202, v176, v202
	v_add_f32_e32 v203, v176, v203
	v_exp_f32_e32 v200, v200
	v_exp_f32_e32 v201, v201
	v_exp_f32_e32 v202, v202
	v_exp_f32_e32 v203, v203
	v_add_f32_e32 v204, v176, v204
	v_add_f32_e32 v205, v176, v205
	v_add_f32_e32 v206, v176, v206
	v_add_f32_e32 v207, v176, v207
	v_exp_f32_e32 v204, v204
	v_exp_f32_e32 v205, v205
	v_exp_f32_e32 v206, v206
	v_exp_f32_e32 v207, v207
	v_add_f32_e32 v208, v176, v208
	v_add_f32_e32 v209, v176, v209
	v_add_f32_e32 v210, v176, v210
	v_add_f32_e32 v211, v176, v211
	v_exp_f32_e32 v208, v208
	v_exp_f32_e32 v209, v209
	v_exp_f32_e32 v210, v210
	v_exp_f32_e32 v211, v211
	s_nop 0
	v_cvt_pk_bf16_f32 v148, v180, v181
	v_cvt_pk_bf16_f32 v149, v182, v183
	v_cvt_pk_bf16_f32 v150, v184, v185
	v_cvt_pk_bf16_f32 v151, v186, v187
	ds_write_b128 v175, v[148:151]
	v_cvt_pk_bf16_f32 v214, v188, v189
	v_cvt_pk_bf16_f32 v215, v190, v191
	v_cvt_pk_bf16_f32 v216, v192, v193
	v_cvt_pk_bf16_f32 v217, v194, v195
	ds_write_b128 v175, v[214:217] offset:16
	v_cvt_pk_bf16_f32 v148, v196, v197
	v_cvt_pk_bf16_f32 v149, v198, v199
	v_cvt_pk_bf16_f32 v150, v200, v201
	v_cvt_pk_bf16_f32 v151, v202, v203
	ds_write_b128 v175, v[148:151] offset:32
	v_cvt_pk_bf16_f32 v214, v204, v205
	v_cvt_pk_bf16_f32 v215, v206, v207
	v_cvt_pk_bf16_f32 v216, v208, v209
	v_cvt_pk_bf16_f32 v217, v210, v211
	ds_write_b128 v175, v[214:217] offset:48
	s_branch .LBB0_213

; __device__ __forceinline__ unsigned pack2(float a, float b) { return (unsigned)f2bf(a) | ((unsigned)f2bf(b) << 16); }
; template <int DH, int MODE>
; __device__ void attn_item(const Params& p, int layer, int b, int blk, int head, char* smem) {
;     ...
;         float other = __shfl_xor(run, 1);
;         float offs = m_run + (half == 0 ? other : 0.f);
; #pragma unroll 2
;         for (int s8 = 0; s8 < 4; ++s8) {
;           float4 va = s4[2 * s8], vb = s4[2 * s8 + 1];
;           float e[8] = {va.x, va.y, va.z, va.w, vb.x, vb.y, vb.z, vb.w};
;           float pv[8];
; #pragma unroll
;           for (int k = 0; k < 8; ++k) {
;             bool valid = (kpb + s8 * 8 + k) < qpos;
;             pv[k] = valid ? __builtin_amdgcn_exp2f(e[k] + offs) : 0.f;
;           }
;           uint4 ov;
;           ov.x = pack2(pv[0], pv[1]); ov.y = pack2(pv[2], pv[3]);
;           ov.z = pack2(pv[4], pv[5]); ov.w = pack2(pv[6], pv[7]);
;           *reinterpret_cast<uint4*>(prow + s8 * 16) = ov;
;         }
.Lsb_p1done_2:
	ds_bpermute_b32 v147, v163, v146
	s_mov_b32 s88, 0
	v_mov_b32_e32 v175, v168
	v_mov_b32_e32 v177, v167
	s_waitcnt lgkmcnt(0)
	v_cndmask_b32_e64 v148, 0, v147, s[14:15]
	v_add_f32_e32 v176, v174, v148
	v_sub_u32_e32 v212, v144, v173
	v_add_u32_e32 v212, 0xffffc040, v212
	v_cmp_lt_i32_e32 vcc, 31, v212
	s_cmp_eq_u64 vcc, exec
	s_cbranch_scc1 .Lsb_p2fast_2
	v_add_f32_e32 v180, v176, v180
	v_add_f32_e32 v181, v176, v181
	v_add_f32_e32 v182, v176, v182
	v_exp_f32_e32 v180, v180
	v_exp_f32_e32 v181, v181
	v_exp_f32_e32 v182, v182
	v_cmp_lt_i32_e32 vcc, 0, v212
	v_cmp_lt_i32_e64 s[92:93], 1, v212
	v_cmp_lt_i32_e64 s[94:95], 2, v212
	v_cndmask_b32_e32 v180, 0, v180, vcc
	v_cndmask_b32_e64 v181, 0, v181, s[92:93]
	v_cndmask_b32_e64 v182, 0, v182, s[94:95]
	v_add_f32_e32 v183, v176, v183
	v_add_f32_e32 v184, v176, v184
	v_add_f32_e32 v185, v176, v185
	v_exp_f32_e32 v183, v183
	v_exp_f32_e32 v184, v184
	v_exp_f32_e32 v185, v185
	v_cmp_lt_i32_e32 vcc, 3, v212
	v_cmp_lt_i32_e64 s[92:93], 4, v212
	v_cmp_lt_i32_e64 s[94:95], 5, v212
	v_cndmask_b32_e32 v183, 0, v183, vcc
	v_cndmask_b32_e64 v184, 0, v184, s[92:93]
	v_cndmask_b32_e64 v185, 0, v185, s[94:95]
	v_add_f32_e32 v186, v176, v186
	v_add_f32_e32 v187, v176, v187
	v_add_f32_e32 v188, v176, v188
	v_exp_f32_e32 v186, v186
	v_exp_f32_e32 v187, v187
	v_exp_f32_e32 v188, v188
	v_cmp_lt_i32_e32 vcc, 6, v212
	v_cmp_lt_i32_e64 s[92:93], 7, v212
	v_cmp_lt_i32_e64 s[94:95], 8, v212
	v_cndmask_b32_e32 v186, 0, v186, vcc
	v_cndmask_b32_e64 v187, 0, v187, s[92:93]
	v_cndmask_b32_e64 v188, 0, v188, s[94:95]
	v_add_f32_e32 v189, v176, v189
	v_add_f32_e32 v190, v176, v190
	v_add_f32_e32 v191, v176, v191
	v_exp_f32_e32 v189, v189
	v_exp_f32_e32 v190, v190
	v_exp_f32_e32 v191, v191
	v_cmp_lt_i32_e32 vcc, 9, v212
	v_cmp_lt_i32_e64 s[92:93], 10, v212
	v_cmp_lt_i32_e64 s[94:95], 11, v212
	v_cndmask_b32_e32 v189, 0, v189, vcc
	v_cndmask_b32_e64 v190, 0, v190, s[92:93]
	v_cndmask_b32_e64 v191, 0, v191, s[94:95]
	v_add_f32_e32 v192, v176, v192
	v_add_f32_e32 v193, v176, v193
	v_add_f32_e32 v194, v176, v194
	v_exp_f32_e32 v192, v192
	v_exp_f32_e32 v193, v193
	v_exp_f32_e32 v194, v194
	v_cmp_lt_i32_e32 vcc, 12, v212
	v_cmp_lt_i32_e64 s[92:93], 13, v212
	v_cmp_lt_i32_e64 s[94:95], 14, v212
	v_cndmask_b32_e32 v192, 0, v192, vcc
	v_cndmask_b32_e64 v193, 0, v193, s[92:93]
	v_cndmask_b32_e64 v194, 0, v194, s[94:95]
	v_add_f32_e32 v195, v176, v195
	v_add_f32_e32 v196, v176, v196
	v_add_f32_e32 v197, v176, v197
	v_exp_f32_e32 v195, v195
	v_exp_f32_e32 v196, v196
	v_exp_f32_e32 v197, v197
	v_cmp_lt_i32_e32 vcc, 15, v212
	v_cmp_lt_i32_e64 s[92:93], 16, v212
	v_cmp_lt_i32_e64 s[94:95], 17, v212
	v_cndmask_b32_e32 v195, 0, v195, vcc
	v_cndmask_b32_e64 v196, 0, v196, s[92:93]
	v_cndmask_b32_e64 v197, 0, v197, s[94:95]
	v_add_f32_e32 v198, v176, v198
	v_add_f32_e32 v199, v176, v199
	v_add_f32_e32 v200, v176, v200
	v_exp_f32_e32 v198, v198
	v_exp_f32_e32 v199, v199
	v_exp_f32_e32 v200, v200
	v_cmp_lt_i32_e32 vcc, 18, v212
	v_cmp_lt_i32_e64 s[92:93], 19, v212
	v_cmp_lt_i32_e64 s[94:95], 20, v212
	v_cndmask_b32_e32 v198, 0, v198, vcc
	v_cndmask_b32_e64 v199, 0, v199, s[92:93]
	v_cndmask_b32_e64 v200, 0, v200, s[94:95]
	v_add_f32_e32 v201, v176, v201
	v_add_f32_e32 v202, v176, v202
	v_add_f32_e32 v203, v176, v203
	v_exp_f32_e32 v201, v201
	v_exp_f32_e32 v202, v202
	v_exp_f32_e32 v203, v203
	v_cmp_lt_i32_e32 vcc, 21, v212
	v_cmp_lt_i32_e64 s[92:93], 22, v212
	v_cmp_lt_i32_e64 s[94:95], 23, v212
	v_cndmask_b32_e32 v201, 0, v201, vcc
	v_cndmask_b32_e64 v202, 0, v202, s[92:93]
	v_cndmask_b32_e64 v203, 0, v203, s[94:95]
	v_add_f32_e32 v204, v176, v204
	v_add_f32_e32 v205, v176, v205
	v_add_f32_e32 v206, v176, v206
	v_exp_f32_e32 v204, v204
	v_exp_f32_e32 v205, v205
	v_exp_f32_e32 v206, v206
	v_cmp_lt_i32_e32 vcc, 24, v212
	v_cmp_lt_i32_e64 s[92:93], 25, v212
	v_cmp_lt_i32_e64 s[94:95], 26, v212
	v_cndmask_b32_e32 v204, 0, v204, vcc
	v_cndmask_b32_e64 v205, 0, v205, s[92:93]
	v_cndmask_b32_e64 v206, 0, v206, s[94:95]
	v_add_f32_e32 v207, v176, v207
	v_add_f32_e32 v208, v176, v208
	v_add_f32_e32 v209, v176, v209
	v_exp_f32_e32 v207, v207
	v_exp_f32_e32 v208, v208
	v_exp_f32_e32 v209, v209
	v_cmp_lt_i32_e32 vcc, 27, v212
	v_cmp_lt_i32_e64 s[92:93], 28, v212
	v_cmp_lt_i32_e64 s[94:95], 29, v212
	v_cndmask_b32_e32 v207, 0, v207, vcc
	v_cndmask_b32_e64 v208, 0, v208, s[92:93]
	v_cndmask_b32_e64 v209, 0, v209, s[94:95]
	v_add_f32_e32 v210, v176, v210
	v_add_f32_e32 v211, v176, v211
	v_exp_f32_e32 v210, v210
	v_exp_f32_e32 v211, v211
	v_cmp_lt_i32_e32 vcc, 30, v212
	v_cmp_lt_i32_e64 s[92:93], 31, v212
	s_nop 0
	v_cndmask_b32_e32 v210, 0, v210, vcc
	v_cndmask_b32_e64 v211, 0, v211, s[92:93]
	v_cvt_pk_bf16_f32 v148, v180, v181
	v_cvt_pk_bf16_f32 v149, v182, v183
	v_cvt_pk_bf16_f32 v150, v184, v185
	v_cvt_pk_bf16_f32 v151, v186, v187
	ds_write_b128 v175, v[148:151]
	v_cvt_pk_bf16_f32 v214, v188, v189
	v_cvt_pk_bf16_f32 v215, v190, v191
	v_cvt_pk_bf16_f32 v216, v192, v193
	v_cvt_pk_bf16_f32 v217, v194, v195
	ds_write_b128 v175, v[214:217] offset:16
	v_cvt_pk_bf16_f32 v148, v196, v197
	v_cvt_pk_bf16_f32 v149, v198, v199
	v_cvt_pk_bf16_f32 v150, v200, v201
	v_cvt_pk_bf16_f32 v151, v202, v203
	ds_write_b128 v175, v[148:151] offset:32
	v_cvt_pk_bf16_f32 v214, v204, v205
	v_cvt_pk_bf16_f32 v215, v206, v207
	v_cvt_pk_bf16_f32 v216, v208, v209
	v_cvt_pk_bf16_f32 v217, v210, v211
	ds_write_b128 v175, v[214:217] offset:48
	s_branch .LBB0_534

; __device__ __forceinline__ unsigned pack2(float a, float b) { return (unsigned)f2bf(a) | ((unsigned)f2bf(b) << 16); }
; template <int DH, int MODE>
; __device__ void attn_item(const Params& p, int layer, int b, int blk, int head, char* smem) {
;     ...
;         float other = __shfl_xor(run, 1);
;         float offs = m_run + (half == 0 ? other : 0.f);
; #pragma unroll 2
;         for (int s8 = 0; s8 < 4; ++s8) {
;           float4 va = s4[2 * s8], vb = s4[2 * s8 + 1];
;           float e[8] = {va.x, va.y, va.z, va.w, vb.x, vb.y, vb.z, vb.w};
;           float pv[8];
; #pragma unroll
;           for (int k = 0; k < 8; ++k) {
;             bool valid = (kpb + s8 * 8 + k) < qpos;
;             pv[k] = valid ? __builtin_amdgcn_exp2f(e[k] + offs) : 0.f;
;           }
;           uint4 ov;
;           ov.x = pack2(pv[0], pv[1]); ov.y = pack2(pv[2], pv[3]);
;           ov.z = pack2(pv[4], pv[5]); ov.w = pack2(pv[6], pv[7]);
;           *reinterpret_cast<uint4*>(prow + s8 * 16) = ov;
;         }
.Lsb_p1done_0:
	ds_bpermute_b32 v147, v163, v146
	s_mov_b32 s81, 0
	v_mov_b32_e32 v175, v168
	v_mov_b32_e32 v177, v167
	s_waitcnt lgkmcnt(0)
	v_cndmask_b32_e64 v148, 0, v147, s[8:9]
	v_add_f32_e32 v176, v174, v148
	v_sub_u32_e32 v212, v144, v173
	v_add_u32_e32 v212, 0xffffc040, v212
	v_cmp_lt_i32_e32 vcc, 31, v212
	s_cmp_eq_u64 vcc, exec
	s_cbranch_scc1 .Lsb_p2fast_0
	v_add_f32_e32 v180, v176, v180
	v_add_f32_e32 v181, v176, v181
	v_add_f32_e32 v182, v176, v182
	v_exp_f32_e32 v180, v180
	v_exp_f32_e32 v181, v181
	v_exp_f32_e32 v182, v182
	v_cmp_lt_i32_e32 vcc, 0, v212
	v_cmp_lt_i32_e64 s[92:93], 1, v212
	v_cmp_lt_i32_e64 s[94:95], 2, v212
	v_cndmask_b32_e32 v180, 0, v180, vcc
	v_cndmask_b32_e64 v181, 0, v181, s[92:93]
	v_cndmask_b32_e64 v182, 0, v182, s[94:95]
	v_add_f32_e32 v183, v176, v183
	v_add_f32_e32 v184, v176, v184
	v_add_f32_e32 v185, v176, v185
	v_exp_f32_e32 v183, v183
	v_exp_f32_e32 v184, v184
	v_exp_f32_e32 v185, v185
	v_cmp_lt_i32_e32 vcc, 3, v212
	v_cmp_lt_i32_e64 s[92:93], 4, v212
	v_cmp_lt_i32_e64 s[94:95], 5, v212
	v_cndmask_b32_e32 v183, 0, v183, vcc
	v_cndmask_b32_e64 v184, 0, v184, s[92:93]
	v_cndmask_b32_e64 v185, 0, v185, s[94:95]
	v_add_f32_e32 v186, v176, v186
	v_add_f32_e32 v187, v176, v187
	v_add_f32_e32 v188, v176, v188
	v_exp_f32_e32 v186, v186
	v_exp_f32_e32 v187, v187
	v_exp_f32_e32 v188, v188
	v_cmp_lt_i32_e32 vcc, 6, v212
	v_cmp_lt_i32_e64 s[92:93], 7, v212
	v_cmp_lt_i32_e64 s[94:95], 8, v212
	v_cndmask_b32_e32 v186, 0, v186, vcc
	v_cndmask_b32_e64 v187, 0, v187, s[92:93]
	v_cndmask_b32_e64 v188, 0, v188, s[94:95]
	v_add_f32_e32 v189, v176, v189
	v_add_f32_e32 v190, v176, v190
	v_add_f32_e32 v191, v176, v191
	v_exp_f32_e32 v189, v189
	v_exp_f32_e32 v190, v190
	v_exp_f32_e32 v191, v191
	v_cmp_lt_i32_e32 vcc, 9, v212
	v_cmp_lt_i32_e64 s[92:93], 10, v212
	v_cmp_lt_i32_e64 s[94:95], 11, v212
	v_cndmask_b32_e32 v189, 0, v189, vcc
	v_cndmask_b32_e64 v190, 0, v190, s[92:93]
	v_cndmask_b32_e64 v191, 0, v191, s[94:95]
	v_add_f32_e32 v192, v176, v192
	v_add_f32_e32 v193, v176, v193
	v_add_f32_e32 v194, v176, v194
	v_exp_f32_e32 v192, v192
	v_exp_f32_e32 v193, v193
	v_exp_f32_e32 v194, v194
	v_cmp_lt_i32_e32 vcc, 12, v212
	v_cmp_lt_i32_e64 s[92:93], 13, v212
	v_cmp_lt_i32_e64 s[94:95], 14, v212
	v_cndmask_b32_e32 v192, 0, v192, vcc
	v_cndmask_b32_e64 v193, 0, v193, s[92:93]
	v_cndmask_b32_e64 v194, 0, v194, s[94:95]
	v_add_f32_e32 v195, v176, v195
	v_add_f32_e32 v196, v176, v196
	v_add_f32_e32 v197, v176, v197
	v_exp_f32_e32 v195, v195
	v_exp_f32_e32 v196, v196
	v_exp_f32_e32 v197, v197
	v_cmp_lt_i32_e32 vcc, 15, v212
	v_cmp_lt_i32_e64 s[92:93], 16, v212
	v_cmp_lt_i32_e64 s[94:95], 17, v212
	v_cndmask_b32_e32 v195, 0, v195, vcc
	v_cndmask_b32_e64 v196, 0, v196, s[92:93]
	v_cndmask_b32_e64 v197, 0, v197, s[94:95]
	v_add_f32_e32 v198, v176, v198
	v_add_f32_e32 v199, v176, v199
	v_add_f32_e32 v200, v176, v200
	v_exp_f32_e32 v198, v198
	v_exp_f32_e32 v199, v199
	v_exp_f32_e32 v200, v200
	v_cmp_lt_i32_e32 vcc, 18, v212
	v_cmp_lt_i32_e64 s[92:93], 19, v212
	v_cmp_lt_i32_e64 s[94:95], 20, v212
	v_cndmask_b32_e32 v198, 0, v198, vcc
	v_cndmask_b32_e64 v199, 0, v199, s[92:93]
	v_cndmask_b32_e64 v200, 0, v200, s[94:95]
	v_add_f32_e32 v201, v176, v201
	v_add_f32_e32 v202, v176, v202
	v_add_f32_e32 v203, v176, v203
	v_exp_f32_e32 v201, v201
	v_exp_f32_e32 v202, v202
	v_exp_f32_e32 v203, v203
	v_cmp_lt_i32_e32 vcc, 21, v212
	v_cmp_lt_i32_e64 s[92:93], 22, v212
	v_cmp_lt_i32_e64 s[94:95], 23, v212
	v_cndmask_b32_e32 v201, 0, v201, vcc
	v_cndmask_b32_e64 v202, 0, v202, s[92:93]
	v_cndmask_b32_e64 v203, 0, v203, s[94:95]
	v_add_f32_e32 v204, v176, v204
	v_add_f32_e32 v205, v176, v205
	v_add_f32_e32 v206, v176, v206
	v_exp_f32_e32 v204, v204
	v_exp_f32_e32 v205, v205
	v_exp_f32_e32 v206, v206
	v_cmp_lt_i32_e32 vcc, 24, v212
	v_cmp_lt_i32_e64 s[92:93], 25, v212
	v_cmp_lt_i32_e64 s[94:95], 26, v212
	v_cndmask_b32_e32 v204, 0, v204, vcc
	v_cndmask_b32_e64 v205, 0, v205, s[92:93]
	v_cndmask_b32_e64 v206, 0, v206, s[94:95]
	v_add_f32_e32 v207, v176, v207
	v_add_f32_e32 v208, v176, v208
	v_add_f32_e32 v209, v176, v209
	v_exp_f32_e32 v207, v207
	v_exp_f32_e32 v208, v208
	v_exp_f32_e32 v209, v209
	v_cmp_lt_i32_e32 vcc, 27, v212
	v_cmp_lt_i32_e64 s[92:93], 28, v212
	v_cmp_lt_i32_e64 s[94:95], 29, v212
	v_cndmask_b32_e32 v207, 0, v207, vcc
	v_cndmask_b32_e64 v208, 0, v208, s[92:93]
	v_cndmask_b32_e64 v209, 0, v209, s[94:95]
	v_add_f32_e32 v210, v176, v210
	v_add_f32_e32 v211, v176, v211
	v_exp_f32_e32 v210, v210
	v_exp_f32_e32 v211, v211
	v_cmp_lt_i32_e32 vcc, 30, v212
	v_cmp_lt_i32_e64 s[92:93], 31, v212
	s_nop 0
	v_cndmask_b32_e32 v210, 0, v210, vcc
	v_cndmask_b32_e64 v211, 0, v211, s[92:93]
	v_cvt_pk_bf16_f32 v148, v180, v181
	v_cvt_pk_bf16_f32 v149, v182, v183
	v_cvt_pk_bf16_f32 v150, v184, v185
	v_cvt_pk_bf16_f32 v151, v186, v187
	ds_write_b128 v175, v[148:151]
	v_cvt_pk_bf16_f32 v214, v188, v189
	v_cvt_pk_bf16_f32 v215, v190, v191
	v_cvt_pk_bf16_f32 v216, v192, v193
	v_cvt_pk_bf16_f32 v217, v194, v195
	ds_write_b128 v175, v[214:217] offset:16
	v_cvt_pk_bf16_f32 v148, v196, v197
	v_cvt_pk_bf16_f32 v149, v198, v199
	v_cvt_pk_bf16_f32 v150, v200, v201
	v_cvt_pk_bf16_f32 v151, v202, v203
	ds_write_b128 v175, v[148:151] offset:32
	v_cvt_pk_bf16_f32 v214, v204, v205
	v_cvt_pk_bf16_f32 v215, v206, v207
	v_cvt_pk_bf16_f32 v216, v208, v209
	v_cvt_pk_bf16_f32 v217, v210, v211
	ds_write_b128 v175, v[214:217] offset:48
	s_branch .LBB0_1176
